# grid barrier far counters now zeroed by WG 0 with device-scope atomic AND 0 instead of plain stores (no cached copy of the counter lines); otherwise as the private-line barrier
# baseline (speedup 1.0000x reference)
; DI void fast_grid_barrier(unsigned* ctr, unsigned target) {
;     asm volatile("s_waitcnt vmcnt(0)" ::: "memory");
;     __syncthreads();
;     if (threadIdx.x == 0) {
;         __builtin_amdgcn_fence(__ATOMIC_RELEASE, "agent");
;         asm volatile("s_waitcnt vmcnt(0)" ::: "memory");
;         __hip_atomic_fetch_add(ctr, 1u, __ATOMIC_RELAXED, __HIP_MEMORY_SCOPE_AGENT);
;         while (__hip_atomic_load(ctr, __ATOMIC_RELAXED, __HIP_MEMORY_SCOPE_AGENT) < target) __builtin_amdgcn_s_sleep(1);
;         __builtin_amdgcn_fence(__ATOMIC_ACQUIRE, "agent");
;         asm volatile("s_waitcnt vmcnt(0)" ::: "memory");
;     }
;     __syncthreads();
; }
.LBB0_4:
	s_cmp_le_i32 s70, s12
	s_cbranch_scc1 .LBB0_26
	v_readlane_b32 s0, v255, 4
	s_cmp_lg_u32 s70, s0
	s_mov_b64 s[0:1], -1
	s_waitcnt vmcnt(0)
	v_readlane_b32 s0, v255, 11
	s_add_i32 s4, s0, 1
	s_barrier
	s_mov_b64 s[0:1], exec
	v_readlane_b32 s6, v255, 12
	v_readlane_b32 s7, v255, 13
	s_and_b64 s[6:7], s[0:1], s[6:7]
	s_mov_b64 exec, s[6:7]
	s_cbranch_execz .LBB0_12
	s_cmp_lg_u32 s4, 1
	s_cbranch_scc1 .Lgb_arrive
	s_cmp_lg_u32 s2, 0
	s_cbranch_scc1 .Lgb_arrive
	v_mov_b32_e32 v1, 0x1000
	global_atomic_and v1, v165, s[14:15]
	global_atomic_and v1, v165, s[14:15] offset:256
	global_atomic_and v1, v165, s[14:15] offset:512
	global_atomic_and v1, v165, s[14:15] offset:768
	global_atomic_and v1, v165, s[14:15] offset:1024
	global_atomic_and v1, v165, s[14:15] offset:1280
	global_atomic_and v1, v165, s[14:15] offset:1536
	global_atomic_and v1, v165, s[14:15] offset:1792
